# one static s_setprio 1 for waves 0-3 at kernel entry (no per-phase flips), on top of ALIGN-barrier removal
# speedup vs baseline: 1.0015x; 1.0015x over previous
; #define LAS __attribute__((address_space(3)))
; __global__ void __launch_bounds__(512, 2) hybrid_fwd(Params Pk) {
;     LAS unsigned char* lds = (LAS unsigned char*)g_lds;
;     cg::grid_group grid = cg::this_grid();
;     if (threadIdx.x < 2) ((LAS unsigned*)(lds + LDS_XB))[threadIdx.x] = 0u;
_Z10hybrid_fwd6Params:
	v_and_b32_e32 v155, 0x3ff, v0
	s_nop 0
	v_readfirstlane_b32 s99, v155
	s_nop 3
	s_lshr_b32 s99, s99, 6
	s_cmp_ge_u32 s99, 4
	s_cbranch_scc1 .Lprio_done
	s_setprio 1
